# v35 + the first two K-fragment LDS reads issued right after the step barrier, above the wave-uniform active branches
# baseline (speedup 1.0000x reference)
; #define LAS __attribute__((address_space(3)))
; #define AT_LOADK(tt) do { const unsigned ko = kgo + (unsigned)(tt) * (64 * BR * 2); ks0 = *(const u32x4*)((const char*)K + ko); ks1 = *(const u32x4*)((const char*)K + ko + 32 * BR * 2); } while (0)
; #define AT_WRITEK(buf) do { *(LAS u32x4*)(lds + (buf) * KT_BYTES + kl) = ks0; *(LAS u32x4*)(lds + (buf) * KT_BYTES + kl + 32 * KROW) = ks1; } while (0)
; template <int HF> ...
;     ...
;         for (int d0 = 0; d0 < 4; ++d0) { const bf16x8 kf = *(const LAS bf16x8*)(kb + HF * 32 * KROW + sub * 128 + d0 * 32);
; __device__ __forceinline__ void attn_unit(int b, int h, int qb, bf16_t* Q, const bf16_t* __restrict__ K, const bf16_t* __restrict__ Vt, const bf16_t* __restrict__ Z, const float* __restrict__ hg, float lam, ...
;     ...
;         if (more) AT_LOADK(t + 1);
;         __builtin_amdgcn_sched_barrier(0);
;         if (active) att_half<0>(o, lsum, qf, kb, vb, slope2, SB, 64 * t, qw0, r32, hi, band, more, ks0, ks1, lds + (cur ^ 1) * KT_BYTES + kl);
;         else if (more) AT_WRITEK(cur ^ 1);
.LBB0_245:
	ds_read_b128 v[248:251], v247
	ds_read_b128 v[252:255], v247 offset:32
	s_mov_b64 s[66:67], -1
	s_andn2_b64 vcc, exec, s[64:65]
	s_cbranch_vccz .LBB0_251
	s_and_b64 vcc, exec, s[8:9]
	s_cbranch_vccnz .LBB0_250
	s_xor_b32 s66, s92, 1
	s_mulk_i32 s66, 0x4400
	v_add_u32_e32 v128, s66, v233
	s_waitcnt vmcnt(3)
	ds_write_b128 v128, v[160:163]
	s_waitcnt vmcnt(2)
	ds_write_b128 v128, v[168:171] offset:8704
	v_add_u32_e32 v128, 0x40000, v210
	v_add_u32_e32 v129, 0x60000, v210
	global_load_dwordx4 v[160:163], v128, s[38:39]
	global_load_dwordx4 v[168:171], v129, s[38:39]

; #define LAS __attribute__((address_space(3)))
; template <int HF> ...
;     ...
;         for (int r = 0; r < 16; ++r) p[r] = __builtin_fmaf(s2v, (float)((r & 3) + 8 * (r >> 2)), tb);
; #pragma unroll
;         for (int d0 = 0; d0 < 4; ++d0) { const bf16x8 kf = *(const LAS bf16x8*)(kb + HF * 32 * KROW + sub * 128 + d0 * 32);
;             p = __builtin_amdgcn_mfma_f32_32x32x16_bf16(kf, qf[sub][d0], p, 0, 0, 0); }
;         if (band) { const int lim = qw0 + r32 - (kvh0 + 4 * hi);
;             asm volatile("s_nop 15" : "+v"(p));
;             const float ninf = -INFINITY;
; #pragma unroll
;             for (int r = 0; r < 16; ++r) asm("v_cmp_gt_i32_e32 vcc, %2, %1\n\tv_cndmask_b32_e32 %0, %0, %3, vcc" : "+v"(p[r]) : "v"(lim), "i"((r & 3) + 8 * (r >> 2)), "v"(ninf) : "vcc"); }
.LBB0_251:
	s_andn2_b64 vcc, exec, s[66:67]
	s_cbranch_vccnz .LBB0_259
	s_and_b64 vcc, exec, s[10:11]
	s_waitcnt vmcnt(7) lgkmcnt(1)
	s_nop 0
	v_mfma_f32_32x32x16_bf16 v[144:159], v[248:251], v[176:179], v[128:143]
	s_waitcnt vmcnt(6) lgkmcnt(0)
	v_mfma_f32_32x32x16_bf16 v[144:159], v[252:255], v[180:183], v[144:159]
	ds_read_b128 v[248:251], v247 offset:64
	ds_read_b128 v[252:255], v247 offset:96
	s_waitcnt vmcnt(5) lgkmcnt(1)
	v_mfma_f32_32x32x16_bf16 v[144:159], v[248:251], v[184:187], v[144:159]
	s_waitcnt vmcnt(4) lgkmcnt(0)
	v_mfma_f32_32x32x16_bf16 v[144:159], v[252:255], v[188:191], v[144:159]
	s_cbranch_vccnz .LBB0_254
	s_nop 15
	s_nop 0
	v_cmp_gt_i32_e32 vcc, 0, v227
	v_cndmask_b32_e32 v144, v144, v244, vcc
	s_nop 0
	v_cmp_gt_i32_e32 vcc, 1, v227
	v_cndmask_b32_e32 v145, v145, v244, vcc
	s_nop 0
	v_cmp_gt_i32_e32 vcc, 2, v227
	v_cndmask_b32_e32 v146, v146, v244, vcc
	s_nop 0
	v_cmp_gt_i32_e32 vcc, 3, v227
	v_cndmask_b32_e32 v147, v147, v244, vcc
	s_nop 0
	v_cmp_gt_i32_e32 vcc, 8, v227
	v_cndmask_b32_e32 v148, v148, v244, vcc
	s_nop 0
	v_cmp_gt_i32_e32 vcc, 9, v227
	v_cndmask_b32_e32 v149, v149, v244, vcc
	s_nop 0
	v_cmp_gt_i32_e32 vcc, 10, v227
	v_cndmask_b32_e32 v150, v150, v244, vcc
	s_nop 0
	v_cmp_gt_i32_e32 vcc, 11, v227
	v_cndmask_b32_e32 v151, v151, v244, vcc
	s_nop 0
	v_cmp_gt_i32_e32 vcc, 16, v227
	v_cndmask_b32_e32 v152, v152, v244, vcc
	s_nop 0
	v_cmp_gt_i32_e32 vcc, 17, v227
	v_cndmask_b32_e32 v153, v153, v244, vcc
	s_nop 0
	v_cmp_gt_i32_e32 vcc, 18, v227
	v_cndmask_b32_e32 v154, v154, v244, vcc
	s_nop 0
	v_cmp_gt_i32_e32 vcc, 19, v227
	v_cndmask_b32_e32 v155, v155, v244, vcc
	s_nop 0
	v_cmp_gt_i32_e32 vcc, 24, v227
	v_cndmask_b32_e32 v156, v156, v244, vcc
	s_nop 0
	v_cmp_gt_i32_e32 vcc, 25, v227
	v_cndmask_b32_e32 v157, v157, v244, vcc
	s_nop 0
	v_cmp_gt_i32_e32 vcc, 26, v227
	v_cndmask_b32_e32 v158, v158, v244, vcc
	s_nop 0
	v_cmp_gt_i32_e32 vcc, 27, v227
	v_cndmask_b32_e32 v159, v159, v244, vcc
